# speedup vs baseline: 1.0195x; 1.0195x over previous
; __device__ __forceinline__ unsigned xb_ld(unsigned* p)              { return __hip_atomic_load(p, __ATOMIC_RELAXED, __HIP_MEMORY_SCOPE_AGENT); }
; __device__ __forceinline__ unsigned xb_add(unsigned* p, unsigned v) { return __hip_atomic_fetch_add(p, v, __ATOMIC_RELAXED, __HIP_MEMORY_SCOPE_AGENT); }
; #define XB_SPIN(cond, bar) do { unsigned _sp = 0; while (cond) { __builtin_amdgcn_s_sleep(1); \
;     if ((++_sp & 255u) == 0u) { if (xb_ld(&(bar)[XB_TMO])) break; if (_sp > XB_SPIN_CAP) { atomicAdd(&(bar)[XB_TMO], 1u); break; } } } } while (0)
; __device__ __forceinline__ void xcd_barrier(const XcdBarrier& b) {
;     ...
;         const unsigned old = xb_add(&bar[XB_XSUB(b.x)], 1u);
;         const unsigned gen = old / nloc;
;         if (old + 1u == (gen + 1u) * nloc) {
;             __builtin_amdgcn_fence(__ATOMIC_RELEASE, "agent");
;             asm volatile("s_waitcnt vmcnt(0)" ::: "memory");
;             const unsigned og = xb_add(&bar[XB_TOP], 1u);
;             const unsigned tg = og / nx;
;             if (og + 1u == (tg + 1u) * nx) xb_add(&bar[XB_TOPGEN], 1u);
;             else XB_SPIN(xb_ld(&bar[XB_TOPGEN]) == tg, bar);
.Llb_go_2:
	s_and_b32 s16, s2, 7
	s_lshl_b32 s16, s16, 8
	s_add_u32 s20, s14, 0x25d05000
	s_addc_u32 s21, s15, 0
	s_add_u32 s20, s20, s16
	s_addc_u32 s21, s21, 0
	v_mov_b32_e32 v2, 0
	v_mov_b32_e32 v3, 1
	global_atomic_add v4, v2, v3, s[20:21] sc0
	buffer_inv sc1
	s_waitcnt vmcnt(1)
	v_readfirstlane_b32 s17, v4
	s_lshr_b32 s22, s17, 5
	s_add_u32 s17, s17, 1
	s_and_b32 s17, s17, 31
	s_cmp_eq_u32 s17, 0
	s_cbranch_scc0 .Llb_wait_2
	global_atomic_add v2, v3, s[20:21] offset:2048
	s_waitcnt vmcnt(1)
	s_branch .LBB0_377

; __device__ __forceinline__ unsigned xb_ld(unsigned* p)              { return __hip_atomic_load(p, __ATOMIC_RELAXED, __HIP_MEMORY_SCOPE_AGENT); }
; #define XB_SPIN(cond, bar) do { unsigned _sp = 0; while (cond) { __builtin_amdgcn_s_sleep(1); \
;     if ((++_sp & 255u) == 0u) { if (xb_ld(&(bar)[XB_TMO])) break; if (_sp > XB_SPIN_CAP) { atomicAdd(&(bar)[XB_TMO], 1u); break; } } } } while (0)
; __device__ __forceinline__ void xcd_barrier(const XcdBarrier& b) {
;     ...
;             XB_SPIN(xb_ld(&bar[XB_XGEN(b.x)]) == gen, bar);
;             __builtin_amdgcn_fence(__ATOMIC_ACQUIRE, "agent");
.Llb_spin_2:
	global_load_dword v4, v2, s[20:21] offset:2048 sc1
	s_waitcnt vmcnt(0)
	v_readfirstlane_b32 s24, v4
	s_cmp_lg_u32 s24, s22
	s_cbranch_scc1 .Llb_acq_2
	s_add_u32 s23, s23, 1
	s_cmp_lt_u32 s23, 0x100000
	s_cbranch_scc1 .Llb_spin_2

; __device__ __forceinline__ unsigned xb_ld(unsigned* p)              { return __hip_atomic_load(p, __ATOMIC_RELAXED, __HIP_MEMORY_SCOPE_AGENT); }
; __device__ __forceinline__ unsigned xb_add(unsigned* p, unsigned v) { return __hip_atomic_fetch_add(p, v, __ATOMIC_RELAXED, __HIP_MEMORY_SCOPE_AGENT); }
; #define XB_SPIN(cond, bar) do { unsigned _sp = 0; while (cond) { __builtin_amdgcn_s_sleep(1); \
;     if ((++_sp & 255u) == 0u) { if (xb_ld(&(bar)[XB_TMO])) break; if (_sp > XB_SPIN_CAP) { atomicAdd(&(bar)[XB_TMO], 1u); break; } } } } while (0)
; __device__ __forceinline__ void xcd_barrier(const XcdBarrier& b) {
;     ...
;         const unsigned old = xb_add(&bar[XB_XSUB(b.x)], 1u);
;         const unsigned gen = old / nloc;
;         if (old + 1u == (gen + 1u) * nloc) {
;             __builtin_amdgcn_fence(__ATOMIC_RELEASE, "agent");
;             asm volatile("s_waitcnt vmcnt(0)" ::: "memory");
;             const unsigned og = xb_add(&bar[XB_TOP], 1u);
;             const unsigned tg = og / nx;
;             if (og + 1u == (tg + 1u) * nx) xb_add(&bar[XB_TOPGEN], 1u);
;             else XB_SPIN(xb_ld(&bar[XB_TOPGEN]) == tg, bar);
.Llb_go_5:
	s_add_u32 s22, s14, 0x25d06000
	s_addc_u32 s23, s15, 0
	v_mov_b32_e32 v2, 0
	v_mov_b32_e32 v3, 1
	global_atomic_add v2, v3, s[22:23]
	s_and_b32 s16, s2, 7
	s_lshl_b32 s16, s16, 8
	s_add_u32 s20, s14, 0x25d05000
	s_addc_u32 s21, s15, 0
	s_add_u32 s20, s20, s16
	s_addc_u32 s21, s21, 0
	v_mov_b32_e32 v2, 0
	v_mov_b32_e32 v3, 1
	global_atomic_add v4, v2, v3, s[20:21] sc0
	buffer_inv sc1
	s_waitcnt vmcnt(1)
	v_readfirstlane_b32 s17, v4
	s_lshr_b32 s22, s17, 5
	s_add_u32 s17, s17, 1
	s_and_b32 s17, s17, 31
	s_cmp_eq_u32 s17, 0
	s_cbranch_scc0 .Llb_wait_5
	global_atomic_add v2, v3, s[20:21] offset:2048
	s_waitcnt vmcnt(1)
	s_branch .LBB0_865
